# v41 + differential-attention unit output stage: sub-norm gain quads loaded once (8 loads) instead of 16 serial load->vmcnt(0) round trips per unit
# speedup vs baseline: 1.0067x; 1.0067x over previous
; __device__ __forceinline__ float shx(float v, int o, int lane) { return __builtin_bit_cast(float, __builtin_amdgcn_ds_bpermute((lane ^ o) << 2, __builtin_bit_cast(int, v))); }
; template <int DK, bool IS_A>
; __device__ __forceinline__ void attn_unit(const Params& P, int l, LAS unsigned char* lds, int b, int grp, int qtok0, int nkeys) {
;     ...
;         if (s == 0) {
;             const float lam = ((const float*)(P.ws + WS_CTL))[CW_LAM + l];
;             const float oml_init = ((const float*)(P.ws + WS_CTL))[CW_LAM + 8 + l];
;             const float* gn = P.diff_norm + (size_t)l * 64;
;             float sa = 0.f, sb = 0.f;
; #pragma unroll
;             for (int r = 0; r < 16; ++r) {
;                 oa0[r] -= lam * X[(wq * 64 + r) * 64 + lane]; oa1[r] -= lam * X[(wq * 64 + 16 + r) * 64 + lane]; sa += oa0[r] * oa0[r] + oa1[r] * oa1[r];
;                 ob0[r] -= lam * X[(wq * 64 + 32 + r) * 64 + lane]; ob1[r] -= lam * X[(wq * 64 + 48 + r) * 64 + lane]; sb += ob0[r] * ob0[r] + ob1[r] * ob1[r]; }
;             sa += shx(sa, 32, lane); sb += shx(sb, 32, lane);
;             { const float rs_ = (1.0f / sqrtf(sa * (1.0f / 64.0f) + RMS_EPS)) * oml_init; AT_OUT(oa0, oa1, qrow, grp * 64, true); }
.LBB0_402:
	s_or_b64 exec, exec, s[10:11]
	v_cmp_gt_u32_e32 vcc, s21, v165
	s_waitcnt lgkmcnt(0)
	s_barrier
	s_and_saveexec_b64 s[10:11], vcc
	s_cbranch_execz .LBB0_404
	v_readlane_b32 s12, v255, 10
	v_readlane_b32 s13, v255, 11
	s_lshl_b32 s64, s8, 1
	v_readlane_b32 s8, v255, 6
	v_readlane_b32 s9, v255, 7
	v_mov_b32_e32 v165, v129
	s_mov_b32 s7, 0x10000
	global_load_dword v14, v129, s[12:13]
	v_readlane_b32 s12, v255, 12
	v_readlane_b32 s13, v255, 13
	s_nop 4
	global_load_dword v15, v129, s[12:13]
	ds_read2st64_b32 v[30:31], v60 offset1:1
	ds_read2st64_b32 v[62:63], v60 offset0:2 offset1:3
	ds_read2st64_b32 v[76:77], v60 offset0:4 offset1:5
	ds_read2st64_b32 v[78:79], v60 offset0:6 offset1:7
	ds_read2st64_b32 v[80:81], v60 offset0:16 offset1:17
	ds_read2st64_b32 v[82:83], v60 offset0:18 offset1:19
	ds_read2st64_b32 v[84:85], v60 offset0:20 offset1:21
	ds_read2st64_b32 v[86:87], v60 offset0:22 offset1:23
	ds_read2st64_b32 v[88:89], v60 offset0:8 offset1:9
	ds_read2st64_b32 v[90:91], v60 offset0:10 offset1:11
	ds_read2st64_b32 v[92:93], v60 offset0:12 offset1:13
	ds_read2st64_b32 v[94:95], v60 offset0:14 offset1:15
	ds_read2st64_b32 v[96:97], v60 offset0:24 offset1:25
	ds_read2st64_b32 v[98:99], v60 offset0:26 offset1:27
	ds_read2st64_b32 v[100:101], v60 offset0:28 offset1:29
	ds_read2st64_b32 v[102:103], v60 offset0:30 offset1:31
	global_load_dwordx4 v[204:207], v162, s[24:25]
	global_load_dwordx4 v[208:211], v162, s[24:25] offset:32
	global_load_dwordx4 v[212:215], v162, s[24:25] offset:64
	global_load_dwordx4 v[216:219], v162, s[24:25] offset:96
	global_load_dwordx4 v[220:223], v162, s[24:25] offset:128
	global_load_dwordx4 v[224:227], v162, s[24:25] offset:160
	global_load_dwordx4 v[228:231], v162, s[24:25] offset:192
	global_load_dwordx4 v[232:235], v162, s[24:25] offset:224
	s_waitcnt vmcnt(8) lgkmcnt(11)
	v_pk_fma_f32 v[48:49], v[14:15], v[80:81], v[48:49] op_sel_hi:[0,1,1] neg_lo:[1,0,0] neg_hi:[1,0,0]
	s_waitcnt lgkmcnt(6)
	v_pk_fma_f32 v[90:91], v[14:15], v[90:91], v[38:39] op_sel_hi:[0,1,1] neg_lo:[1,0,0] neg_hi:[1,0,0]
	s_waitcnt lgkmcnt(2)
	v_pk_fma_f32 v[98:99], v[14:15], v[98:99], v[40:41] op_sel_hi:[0,1,1] neg_lo:[1,0,0] neg_hi:[1,0,0]
	s_waitcnt lgkmcnt(1)
	v_pk_fma_f32 v[38:39], v[14:15], v[100:101], v[44:45] op_sel_hi:[0,1,1] neg_lo:[1,0,0] neg_hi:[1,0,0]
	s_waitcnt lgkmcnt(0)
	v_pk_fma_f32 v[40:41], v[14:15], v[102:103], v[46:47] op_sel_hi:[0,1,1] neg_lo:[1,0,0] neg_hi:[1,0,0]
	v_pk_fma_f32 v[44:45], v[14:15], v[30:31], v[64:65] op_sel_hi:[0,1,1] neg_lo:[1,0,0] neg_hi:[1,0,0]
	v_pk_fma_f32 v[46:47], v[14:15], v[78:79], v[70:71] op_sel_hi:[0,1,1] neg_lo:[1,0,0] neg_hi:[1,0,0]
	v_pk_fma_f32 v[50:51], v[14:15], v[82:83], v[50:51] op_sel_hi:[0,1,1] neg_lo:[1,0,0] neg_hi:[1,0,0]
	v_pk_mul_f32 v[70:71], v[48:49], v[48:49]
	v_pk_fma_f32 v[92:93], v[14:15], v[92:93], v[42:43] op_sel_hi:[0,1,1] neg_lo:[1,0,0] neg_hi:[1,0,0]
	v_pk_fma_f32 v[42:43], v[14:15], v[62:63], v[66:67] op_sel_hi:[0,1,1] neg_lo:[1,0,0] neg_hi:[1,0,0]
	v_pk_fma_f32 v[62:63], v[14:15], v[76:77], v[68:69] op_sel_hi:[0,1,1] neg_lo:[1,0,0] neg_hi:[1,0,0]
	v_pk_mul_f32 v[68:69], v[50:51], v[50:51]
	v_pk_fma_f32 v[70:71], v[44:45], v[44:45], v[70:71]
	v_pk_fma_f32 v[36:37], v[14:15], v[84:85], v[36:37] op_sel_hi:[0,1,1] neg_lo:[1,0,0] neg_hi:[1,0,0]
	v_pk_fma_f32 v[68:69], v[42:43], v[42:43], v[68:69]
	v_add_f32_e32 v61, v70, v71
	v_pk_mul_f32 v[78:79], v[36:37], v[36:37]
	v_add_f32_e32 v61, v61, v68
	v_pk_fma_f32 v[52:53], v[14:15], v[86:87], v[52:53] op_sel_hi:[0,1,1] neg_lo:[1,0,0] neg_hi:[1,0,0]
	v_pk_fma_f32 v[78:79], v[62:63], v[62:63], v[78:79]
	v_add_f32_e32 v61, v61, v69
	v_pk_mul_f32 v[76:77], v[52:53], v[52:53]
	v_add_f32_e32 v61, v61, v78
	v_pk_fma_f32 v[54:55], v[14:15], v[96:97], v[54:55] op_sel_hi:[0,1,1] neg_lo:[1,0,0] neg_hi:[1,0,0]
	v_pk_fma_f32 v[76:77], v[46:47], v[46:47], v[76:77]
	v_add_f32_e32 v61, v61, v79
	v_pk_fma_f32 v[56:57], v[14:15], v[88:89], v[56:57] op_sel_hi:[0,1,1] neg_lo:[1,0,0] neg_hi:[1,0,0]
	v_pk_mul_f32 v[80:81], v[54:55], v[54:55]
	v_add_f32_e32 v61, v61, v76
	v_pk_fma_f32 v[80:81], v[56:57], v[56:57], v[80:81]
	v_add_f32_e32 v61, v61, v77
	v_pk_mul_f32 v[30:31], v[98:99], v[98:99]
	v_add_f32_e32 v61, v61, v80
	v_pk_fma_f32 v[30:31], v[90:91], v[90:91], v[30:31]
	v_add_f32_e32 v61, v61, v81
	v_pk_mul_f32 v[64:65], v[38:39], v[38:39]
	v_add_f32_e32 v30, v61, v30
	v_pk_fma_f32 v[64:65], v[92:93], v[92:93], v[64:65]
	v_add_f32_e32 v30, v30, v31
	v_pk_fma_f32 v[58:59], v[14:15], v[94:95], v[58:59] op_sel_hi:[0,1,1] neg_lo:[1,0,0] neg_hi:[1,0,0]
	v_pk_mul_f32 v[66:67], v[40:41], v[40:41]
	v_add_f32_e32 v30, v30, v64
	v_pk_fma_f32 v[66:67], v[58:59], v[58:59], v[66:67]
	v_add_f32_e32 v30, v30, v65
	v_add_f32_e32 v30, v30, v66
	v_add_f32_e32 v61, v30, v67
	ds_bpermute_b32 v64, v163, v61
	v_lshlrev_b64 v[30:31], 11, v[128:129]
	v_lshl_add_u64 v[30:31], s[8:9], 0, v[30:31]
	v_lshl_add_u64 v[30:31], v[30:31], 0, s[64:65]
	v_lshl_add_u64 v[30:31], v[30:31], 0, v[164:165]
	s_waitcnt lgkmcnt(0)
	v_add_f32_e32 v61, v61, v64
	v_fmamk_f32 v61, v61, 0x3c800000, v201
	v_mul_f32_e32 v64, 0x4f800000, v61
	v_cmp_gt_f32_e32 vcc, s6, v61
	s_nop 1
	v_cndmask_b32_e32 v61, v61, v64, vcc
	v_sqrt_f32_e32 v64, v61
	s_nop 0
	v_add_u32_e32 v65, -1, v64
	v_add_u32_e32 v66, 1, v64
	v_fma_f32 v67, -v65, v64, v61
	v_fma_f32 v68, -v66, v64, v61
	v_cmp_ge_f32_e64 s[38:39], 0, v67
	s_nop 1
	v_cndmask_b32_e64 v64, v64, v65, s[38:39]
	v_cmp_lt_f32_e64 s[38:39], 0, v68
	s_nop 1
	v_cndmask_b32_e64 v64, v64, v66, s[38:39]
	v_mul_f32_e32 v65, 0x37800000, v64
	v_cndmask_b32_e32 v64, v64, v65, vcc
	v_cmp_class_f32_e32 vcc, v61, v202
	s_nop 1
	v_cndmask_b32_e32 v61, v64, v61, vcc
	v_div_scale_f32 v64, s[8:9], v61, v61, 1.0
	v_rcp_f32_e32 v65, v64
	v_div_scale_f32 v66, vcc, 1.0, v61, 1.0
	v_fma_f32 v67, -v64, v65, 1.0
	v_fmac_f32_e32 v65, v67, v65
	v_mul_f32_e32 v67, v66, v65
	v_fma_f32 v68, -v64, v67, v66
	v_fmac_f32_e32 v67, v68, v65
	v_fma_f32 v64, -v64, v67, v66
	v_div_fmas_f32 v64, v64, v65, v67
	v_div_fixup_f32 v61, v64, v61, 1.0
	v_mul_f32_e32 v64, v15, v61
	s_waitcnt vmcnt(0)
; template <int DK, bool IS_A>
; __device__ __forceinline__ void attn_unit(const Params& P, int l, LAS unsigned char* lds, int b, int grp, int qtok0, int nkeys) {
;     ...
;             for (int r = 0; r < 16; ++r) {
;                 oa0[r] -= lam * X[(wq * 64 + r) * 64 + lane]; oa1[r] -= lam * X[(wq * 64 + 16 + r) * 64 + lane]; sa += oa0[r] * oa0[r] + oa1[r] * oa1[r];
;                 ob0[r] -= lam * X[(wq * 64 + 32 + r) * 64 + lane]; ob1[r] -= lam * X[(wq * 64 + 48 + r) * 64 + lane]; sb += ob0[r] * ob0[r] + ob1[r] * ob1[r]; }
	v_mov_b32_e32 v72, v204
	v_mov_b32_e32 v73, v205
	v_mov_b32_e32 v74, v206
	v_mov_b32_e32 v75, v207
	v_pk_mul_f32 v[66:67], v[74:75], v[64:65] op_sel_hi:[1,0]
	v_pk_mul_f32 v[68:69], v[72:73], v[64:65] op_sel_hi:[1,0]
	v_pk_mul_f32 v[42:43], v[42:43], v[66:67]
	v_pk_mul_f32 v[44:45], v[44:45], v[68:69]
	s_nop 0
	v_cvt_pk_bf16_f32 v44, v44, v45
	v_cvt_pk_bf16_f32 v45, v42, v43
	global_store_dwordx2 v[30:31], v[44:45], off
	v_mov_b32_e32 v42, v208
	v_mov_b32_e32 v43, v209
	v_mov_b32_e32 v44, v210
	v_mov_b32_e32 v45, v211
	v_pk_mul_f32 v[44:45], v[44:45], v[64:65] op_sel_hi:[1,0]
	v_pk_mul_f32 v[42:43], v[42:43], v[64:65] op_sel_hi:[1,0]
	v_pk_mul_f32 v[44:45], v[46:47], v[44:45]
	v_pk_mul_f32 v[42:43], v[62:63], v[42:43]
	s_nop 0
	v_cvt_pk_bf16_f32 v42, v42, v43
	v_cvt_pk_bf16_f32 v43, v44, v45
	global_store_dwordx2 v[30:31], v[42:43], off offset:16
	v_mov_b32_e32 v42, v212
	v_mov_b32_e32 v43, v213
	v_mov_b32_e32 v44, v214
	v_mov_b32_e32 v45, v215
	v_pk_mul_f32 v[44:45], v[44:45], v[64:65] op_sel_hi:[1,0]
	v_pk_mul_f32 v[42:43], v[42:43], v[64:65] op_sel_hi:[1,0]
	v_pk_mul_f32 v[44:45], v[90:91], v[44:45]
	v_pk_mul_f32 v[42:43], v[56:57], v[42:43]
	s_nop 0
	v_cvt_pk_bf16_f32 v42, v42, v43
	v_cvt_pk_bf16_f32 v43, v44, v45
	global_store_dwordx2 v[30:31], v[42:43], off offset:32
	v_mov_b32_e32 v42, v216
	v_mov_b32_e32 v43, v217
	v_mov_b32_e32 v44, v218
	v_mov_b32_e32 v45, v219
	v_pk_mul_f32 v[44:45], v[44:45], v[64:65] op_sel_hi:[1,0]
	v_pk_mul_f32 v[42:43], v[42:43], v[64:65] op_sel_hi:[1,0]
	v_pk_mul_f32 v[44:45], v[58:59], v[44:45]
	v_pk_mul_f32 v[42:43], v[92:93], v[42:43]
	s_nop 0
	v_cvt_pk_bf16_f32 v42, v42, v43
	v_cvt_pk_bf16_f32 v43, v44, v45
	global_store_dwordx2 v[30:31], v[42:43], off offset:48
	v_mov_b32_e32 v42, v220
	v_mov_b32_e32 v43, v221
	v_mov_b32_e32 v44, v222
	v_mov_b32_e32 v45, v223
	v_pk_mul_f32 v[44:45], v[64:65], v[44:45] op_sel_hi:[0,1]
	v_pk_mul_f32 v[42:43], v[64:65], v[42:43] op_sel_hi:[0,1]
	v_pk_mul_f32 v[42:43], v[48:49], v[42:43]
	v_pk_mul_f32 v[44:45], v[50:51], v[44:45]
	v_cvt_pk_bf16_f32 v42, v42, v43
	v_cvt_pk_bf16_f32 v43, v44, v45
	global_store_dwordx2 v[30:31], v[42:43], off offset:64
	v_mov_b32_e32 v42, v224
	v_mov_b32_e32 v43, v225
	v_mov_b32_e32 v44, v226
	v_mov_b32_e32 v45, v227
	v_pk_mul_f32 v[44:45], v[64:65], v[44:45] op_sel_hi:[0,1]
	v_pk_mul_f32 v[42:43], v[64:65], v[42:43] op_sel_hi:[0,1]
	v_pk_mul_f32 v[36:37], v[36:37], v[42:43]
	v_pk_mul_f32 v[42:43], v[52:53], v[44:45]
	v_cvt_pk_bf16_f32 v36, v36, v37
	v_cvt_pk_bf16_f32 v37, v42, v43
	global_store_dwordx2 v[30:31], v[36:37], off offset:80
	v_mov_b32_e32 v42, v228
	v_mov_b32_e32 v43, v229
	v_mov_b32_e32 v44, v230
	v_mov_b32_e32 v45, v231
	v_pk_mul_f32 v[36:37], v[64:65], v[44:45] op_sel_hi:[0,1]
	v_pk_mul_f32 v[42:43], v[64:65], v[42:43] op_sel_hi:[0,1]
	v_pk_mul_f32 v[42:43], v[54:55], v[42:43]
	v_pk_mul_f32 v[36:37], v[98:99], v[36:37]
	v_cvt_pk_bf16_f32 v42, v42, v43
	v_cvt_pk_bf16_f32 v43, v36, v37
	global_store_dwordx2 v[30:31], v[42:43], off offset:96
	v_mov_b32_e32 v42, v232
	v_mov_b32_e32 v43, v233
	v_mov_b32_e32 v44, v234
	v_mov_b32_e32 v45, v235
	ds_read2st64_b32 v[46:47], v60 offset0:32 offset1:33
	ds_read2st64_b32 v[48:49], v60 offset0:34 offset1:35
	ds_read2st64_b32 v[50:51], v60 offset0:36 offset1:37
	ds_read2st64_b32 v[52:53], v60 offset0:38 offset1:39
	ds_read2st64_b32 v[54:55], v60 offset0:48 offset1:49
	ds_read2st64_b32 v[56:57], v60 offset0:50 offset1:51
	ds_read2st64_b32 v[58:59], v60 offset0:52 offset1:53
	ds_read2st64_b32 v[62:63], v60 offset0:54 offset1:55
	ds_read2st64_b32 v[66:67], v60 offset0:40 offset1:41
	ds_read2st64_b32 v[36:37], v60 offset0:42 offset1:43
	ds_read2st64_b32 v[68:69], v60 offset0:44 offset1:45
	ds_read2st64_b32 v[70:71], v60 offset0:46 offset1:47
	ds_read2st64_b32 v[72:73], v60 offset0:58 offset1:59
	ds_read2st64_b32 v[74:75], v60 offset0:60 offset1:61
	ds_read2st64_b32 v[76:77], v60 offset0:62 offset1:63
	ds_read2st64_b32 v[60:61], v60 offset0:56 offset1:57
	s_waitcnt lgkmcnt(6)
	v_pk_fma_f32 v[78:79], v[14:15], v[36:37], v[8:9] op_sel_hi:[0,1,1] neg_lo:[1,0,0] neg_hi:[1,0,0]
	s_waitcnt lgkmcnt(3)
	v_pk_fma_f32 v[36:37], v[14:15], v[72:73], v[10:11] op_sel_hi:[0,1,1] neg_lo:[1,0,0] neg_hi:[1,0,0]
	s_waitcnt lgkmcnt(2)
	v_pk_fma_f32 v[8:9], v[14:15], v[74:75], v[12:13] op_sel_hi:[0,1,1] neg_lo:[1,0,0] neg_hi:[1,0,0]
	v_pk_fma_f32 v[12:13], v[14:15], v[70:71], v[26:27] op_sel_hi:[0,1,1] neg_lo:[1,0,0] neg_hi:[1,0,0]
	s_waitcnt lgkmcnt(1)
	v_pk_fma_f32 v[10:11], v[14:15], v[76:77], v[28:29] op_sel_hi:[0,1,1] neg_lo:[1,0,0] neg_hi:[1,0,0]
	v_pk_fma_f32 v[26:27], v[14:15], v[48:49], v[34:35] op_sel_hi:[0,1,1] neg_lo:[1,0,0] neg_hi:[1,0,0]
	v_pk_fma_f32 v[28:29], v[14:15], v[46:47], v[32:33] op_sel_hi:[0,1,1] neg_lo:[1,0,0] neg_hi:[1,0,0]
	v_pk_fma_f32 v[32:33], v[14:15], v[56:57], v[18:19] op_sel_hi:[0,1,1] neg_lo:[1,0,0] neg_hi:[1,0,0]
	v_pk_fma_f32 v[34:35], v[14:15], v[54:55], v[16:17] op_sel_hi:[0,1,1] neg_lo:[1,0,0] neg_hi:[1,0,0]
	v_pk_mul_f32 v[46:47], v[34:35], v[34:35]
	v_pk_fma_f32 v[24:25], v[14:15], v[68:69], v[24:25] op_sel_hi:[0,1,1] neg_lo:[1,0,0] neg_hi:[1,0,0]
	v_pk_fma_f32 v[46:47], v[28:29], v[28:29], v[46:47]
	v_pk_fma_f32 v[22:23], v[14:15], v[52:53], v[22:23] op_sel_hi:[0,1,1] neg_lo:[1,0,0] neg_hi:[1,0,0]
	v_pk_fma_f32 v[20:21], v[14:15], v[50:51], v[20:21] op_sel_hi:[0,1,1] neg_lo:[1,0,0] neg_hi:[1,0,0]
	v_pk_fma_f32 v[6:7], v[14:15], v[66:67], v[6:7] op_sel_hi:[0,1,1] neg_lo:[1,0,0] neg_hi:[1,0,0]
	s_waitcnt lgkmcnt(0)
; __device__ __forceinline__ float shx(float v, int o, int lane) { return __builtin_bit_cast(float, __builtin_amdgcn_ds_bpermute((lane ^ o) << 2, __builtin_bit_cast(int, v))); }
; template <int DK, bool IS_A>
; __device__ __forceinline__ void attn_unit(const Params& P, int l, LAS unsigned char* lds, int b, int grp, int qtok0, int nkeys) {
;     ...
;                 ob0[r] -= lam * X[(wq * 64 + 32 + r) * 64 + lane]; ob1[r] -= lam * X[(wq * 64 + 48 + r) * 64 + lane]; sb += ob0[r] * ob0[r] + ob1[r] * ob1[r]; }
;             sa += shx(sa, 32, lane); sb += shx(sb, 32, lane);
;             { const float rs_ = (1.0f / sqrtf(sa * (1.0f / 64.0f) + RMS_EPS)) * oml_init; AT_OUT(oa0, oa1, qrow, grp * 64, true); }
;             { const float rs_ = (1.0f / sqrtf(sb * (1.0f / 64.0f) + RMS_EPS)) * oml_init; AT_OUT(ob0, ob1, qrow + 32, grp * 64, true); }
	v_pk_fma_f32 v[4:5], v[14:15], v[60:61], v[4:5] op_sel_hi:[0,1,1] neg_lo:[1,0,0] neg_hi:[1,0,0]
	v_pk_mul_f32 v[52:53], v[4:5], v[4:5]
	v_pk_mul_f32 v[16:17], v[64:65], v[44:45] op_sel_hi:[0,1]
	v_pk_mul_f32 v[18:19], v[64:65], v[42:43] op_sel_hi:[0,1]
	v_pk_mul_f32 v[18:19], v[38:39], v[18:19]
	v_pk_mul_f32 v[16:17], v[40:41], v[16:17]
	v_cvt_pk_bf16_f32 v18, v18, v19
	v_cvt_pk_bf16_f32 v19, v16, v17
	global_store_dwordx2 v[30:31], v[18:19], off offset:112
	v_mov_b32_e32 v16, v204
	v_mov_b32_e32 v17, v205
	v_mov_b32_e32 v18, v206
	v_mov_b32_e32 v19, v207
	v_pk_mul_f32 v[44:45], v[32:33], v[32:33]
	v_pk_fma_f32 v[38:39], v[14:15], v[62:63], v[2:3] op_sel_hi:[0,1,1] neg_lo:[1,0,0] neg_hi:[1,0,0]
	v_pk_fma_f32 v[40:41], v[14:15], v[58:59], v[0:1] op_sel_hi:[0,1,1] neg_lo:[1,0,0] neg_hi:[1,0,0]
	v_pk_fma_f32 v[44:45], v[26:27], v[26:27], v[44:45]
	v_add_f32_e32 v14, v46, v47
	v_pk_mul_f32 v[50:51], v[40:41], v[40:41]
	v_add_f32_e32 v14, v14, v44
	v_pk_fma_f32 v[50:51], v[20:21], v[20:21], v[50:51]
	v_add_f32_e32 v14, v14, v45
	v_pk_mul_f32 v[48:49], v[38:39], v[38:39]
	v_add_f32_e32 v14, v14, v50
	v_pk_fma_f32 v[48:49], v[22:23], v[22:23], v[48:49]
	v_add_f32_e32 v14, v14, v51
	v_add_f32_e32 v14, v14, v48
	v_pk_fma_f32 v[52:53], v[6:7], v[6:7], v[52:53]
	v_add_f32_e32 v14, v14, v49
	v_pk_mul_f32 v[0:1], v[36:37], v[36:37]
	v_add_f32_e32 v14, v14, v52
	v_pk_fma_f32 v[0:1], v[78:79], v[78:79], v[0:1]
	v_add_f32_e32 v14, v14, v53
	v_pk_mul_f32 v[2:3], v[8:9], v[8:9]
	v_add_f32_e32 v0, v14, v0
	v_pk_fma_f32 v[2:3], v[24:25], v[24:25], v[2:3]
	v_add_f32_e32 v0, v0, v1
	v_pk_mul_f32 v[42:43], v[10:11], v[10:11]
	v_add_f32_e32 v0, v0, v2
	v_pk_fma_f32 v[42:43], v[12:13], v[12:13], v[42:43]
	v_add_f32_e32 v0, v0, v3
	v_add_f32_e32 v0, v0, v42
	v_add_f32_e32 v0, v0, v43
	ds_bpermute_b32 v1, v163, v0
	s_waitcnt lgkmcnt(0)
	v_add_f32_e32 v0, v0, v1
	v_fmamk_f32 v0, v0, 0x3c800000, v201
	v_mul_f32_e32 v1, 0x4f800000, v0
	v_cmp_gt_f32_e32 vcc, s6, v0
	s_nop 1
	v_cndmask_b32_e32 v0, v0, v1, vcc
	v_sqrt_f32_e32 v1, v0
	s_nop 0
	v_add_u32_e32 v2, -1, v1
	v_add_u32_e32 v3, 1, v1
	v_fma_f32 v14, -v2, v1, v0
	v_fma_f32 v42, -v3, v1, v0
	v_cmp_ge_f32_e64 s[38:39], 0, v14
	s_nop 1
	v_cndmask_b32_e64 v1, v1, v2, s[38:39]
	v_cmp_lt_f32_e64 s[38:39], 0, v42
	s_nop 1
	v_cndmask_b32_e64 v1, v1, v3, s[38:39]
	v_mul_f32_e32 v2, 0x37800000, v1
	v_cndmask_b32_e32 v1, v1, v2, vcc
	v_cmp_class_f32_e32 vcc, v0, v202
	s_nop 1
	v_cndmask_b32_e32 v2, v1, v0, vcc
	v_div_scale_f32 v3, s[8:9], v2, v2, 1.0
	v_rcp_f32_e32 v14, v3
	v_add_co_u32_e32 v0, vcc, s7, v30
	s_mov_b64 s[8:9], 0x10000
	s_nop 0
	v_addc_co_u32_e32 v1, vcc, 0, v31, vcc
	v_fma_f32 v43, -v3, v14, 1.0
	v_div_scale_f32 v42, vcc, 1.0, v2, 1.0
	v_fmac_f32_e32 v14, v43, v14
	v_mul_f32_e32 v43, v42, v14
	v_fma_f32 v44, -v3, v43, v42
	v_fmac_f32_e32 v43, v44, v14
	v_fma_f32 v3, -v3, v43, v42
	v_div_fmas_f32 v3, v3, v14, v43
	v_div_fixup_f32 v2, v3, v2, 1.0
	v_mul_f32_e32 v14, v15, v2
	v_pk_mul_f32 v[2:3], v[14:15], v[18:19] op_sel_hi:[0,1]
	v_pk_mul_f32 v[16:17], v[14:15], v[16:17] op_sel_hi:[0,1]
	v_pk_mul_f32 v[16:17], v[28:29], v[16:17]
	v_pk_mul_f32 v[2:3], v[26:27], v[2:3]
	v_cvt_pk_bf16_f32 v16, v16, v17
	v_cvt_pk_bf16_f32 v17, v2, v3
	global_store_dwordx2 v[0:1], v[16:17], off
	v_mov_b32_e32 v0, v208
	v_mov_b32_e32 v1, v209
	v_mov_b32_e32 v2, v210
	v_mov_b32_e32 v3, v211
	v_lshl_add_u64 v[16:17], v[30:31], 0, s[8:9]
	v_pk_mul_f32 v[2:3], v[14:15], v[2:3] op_sel_hi:[0,1]
	v_pk_mul_f32 v[0:1], v[14:15], v[0:1] op_sel_hi:[0,1]
	v_pk_mul_f32 v[0:1], v[20:21], v[0:1]
	v_pk_mul_f32 v[2:3], v[22:23], v[2:3]
	v_cvt_pk_bf16_f32 v0, v0, v1
	v_cvt_pk_bf16_f32 v1, v2, v3
	global_store_dwordx2 v[16:17], v[0:1], off offset:16
	v_mov_b32_e32 v0, v212
	v_mov_b32_e32 v1, v213
	v_mov_b32_e32 v2, v214
	v_mov_b32_e32 v3, v215
	v_pk_mul_f32 v[2:3], v[14:15], v[2:3] op_sel_hi:[0,1]
	v_pk_mul_f32 v[0:1], v[14:15], v[0:1] op_sel_hi:[0,1]
	v_pk_mul_f32 v[0:1], v[6:7], v[0:1]
	v_pk_mul_f32 v[2:3], v[78:79], v[2:3]
	v_cvt_pk_bf16_f32 v0, v0, v1
	v_cvt_pk_bf16_f32 v1, v2, v3
	global_store_dwordx2 v[16:17], v[0:1], off offset:32
	v_mov_b32_e32 v0, v216
	v_mov_b32_e32 v1, v217
	v_mov_b32_e32 v2, v218
	v_mov_b32_e32 v3, v219
	v_pk_mul_f32 v[2:3], v[14:15], v[2:3] op_sel_hi:[0,1]
	v_pk_mul_f32 v[0:1], v[14:15], v[0:1] op_sel_hi:[0,1]
	v_pk_mul_f32 v[0:1], v[24:25], v[0:1]
	v_pk_mul_f32 v[2:3], v[12:13], v[2:3]
	v_cvt_pk_bf16_f32 v0, v0, v1
	v_cvt_pk_bf16_f32 v1, v2, v3
	global_store_dwordx2 v[16:17], v[0:1], off offset:48
	v_mov_b32_e32 v0, v220
	v_mov_b32_e32 v1, v221
	v_mov_b32_e32 v2, v222
	v_mov_b32_e32 v3, v223
	v_pk_mul_f32 v[2:3], v[14:15], v[2:3] op_sel_hi:[0,1]
	v_pk_mul_f32 v[0:1], v[14:15], v[0:1] op_sel_hi:[0,1]
	v_pk_mul_f32 v[0:1], v[34:35], v[0:1]
	v_pk_mul_f32 v[2:3], v[32:33], v[2:3]
	v_cvt_pk_bf16_f32 v0, v0, v1
	v_cvt_pk_bf16_f32 v1, v2, v3
	global_store_dwordx2 v[16:17], v[0:1], off offset:64
	v_mov_b32_e32 v0, v224
	v_mov_b32_e32 v1, v225
	v_mov_b32_e32 v2, v226
	v_mov_b32_e32 v3, v227
	v_pk_mul_f32 v[2:3], v[14:15], v[2:3] op_sel_hi:[0,1]
	v_pk_mul_f32 v[0:1], v[14:15], v[0:1] op_sel_hi:[0,1]
	v_pk_mul_f32 v[0:1], v[40:41], v[0:1]
	v_pk_mul_f32 v[2:3], v[38:39], v[2:3]
	v_cvt_pk_bf16_f32 v0, v0, v1
	v_cvt_pk_bf16_f32 v1, v2, v3
	global_store_dwordx2 v[16:17], v[0:1], off offset:80
	v_mov_b32_e32 v0, v228
	v_mov_b32_e32 v1, v229
	v_mov_b32_e32 v2, v230
	v_mov_b32_e32 v3, v231
	v_pk_mul_f32 v[2:3], v[14:15], v[2:3] op_sel_hi:[0,1]
	v_pk_mul_f32 v[0:1], v[14:15], v[0:1] op_sel_hi:[0,1]
	v_pk_mul_f32 v[0:1], v[4:5], v[0:1]
	v_pk_mul_f32 v[2:3], v[36:37], v[2:3]
	v_cvt_pk_bf16_f32 v0, v0, v1
	v_cvt_pk_bf16_f32 v1, v2, v3
	global_store_dwordx2 v[16:17], v[0:1], off offset:96
	v_mov_b32_e32 v0, v232
	v_mov_b32_e32 v1, v233
	v_mov_b32_e32 v2, v234
	v_mov_b32_e32 v3, v235
	v_pk_mul_f32 v[2:3], v[14:15], v[2:3] op_sel_hi:[0,1]
	v_pk_mul_f32 v[0:1], v[14:15], v[0:1] op_sel_hi:[0,1]
	v_pk_mul_f32 v[0:1], v[8:9], v[0:1]
	v_pk_mul_f32 v[2:3], v[10:11], v[2:3]
	v_cvt_pk_bf16_f32 v0, v0, v1
	v_cvt_pk_bf16_f32 v1, v2, v3
	global_store_dwordx2 v[16:17], v[0:1], off offset:112
